# attention: waves 4-7 take the per-tile barrier at the next tile top, waves 0-3 mid exp-block -> the two waves of each SIMD run half a tile out of phase
# speedup vs baseline: 1.0002x; 1.0002x over previous
; template <int MODE> ...
;     ...
;   __syncthreads();
;   *(uint4*)&Kbase[kwoff] = kr0;
;   *(uint4*)&Kbase[64 * 64 + vwoff] = vr0;
;   for (int it = 0; it < ntile; ++it) {
;     const int kt0 = (it < na) ? ka0 + it * 64 : kb0 + (it - na) * 64;
;     const bool masked = window && (it < na);
;     const u16* Ks = Kbase + (it & 1) * (2 * 64 * 64);
;     const u16* Vs = Ks + 64 * 64;
;     __syncthreads();
;     const bool more = it + 1 < ntile;
;     if (more) {
.LBB0_862:
	v_readfirstlane_b32 s99, v195
	s_lshr_b32 s99, s99, 8
	s_waitcnt lgkmcnt(0)
	s_barrier
	s_branch .Lpp1_top
.Lattn1_top:
	s_cmp_eq_u32 s99, 0
	s_cbranch_scc1 .Lpp1_top
	s_barrier

; template <int MODE> ...
;     ...
;     if (more) {
;       u16* Kn = Kbase + ((it + 1) & 1) * (2 * 64 * 64);
;       *(uint4*)&Kn[kwoff] = kr0;
;       *(uint4*)&Kn[64 * 64 + vwoff] = vr0;
;     }
;   }
.LBB0_867:
	s_and_b32 s56, s2, 0x2000
	s_lshl_b32 s56, s56, 1
	s_add_i32 s56, s56, 32
	v_lshl_add_u32 v108, v3, 1, s56
	v_lshl_add_u32 v0, v229, 1, s56
	s_waitcnt vmcnt(1)
	ds_write_b128 v108, v[100:103]
	s_waitcnt vmcnt(0)
	ds_write_b128 v0, v[104:107] offset:8192
	s_waitcnt lgkmcnt(0)
	s_cmp_lg_u32 s99, 0
	s_cbranch_scc1 .Lpp1_skp
	s_barrier
.Lpp1_skp:
.Lattn1_adv:
	s_addk_i32 s2, 0x2000
	s_add_i32 s65, s65, 64
	s_cmp_lg_u32 s45, s66
	s_cbranch_scc1 .LBB0_875
	s_branch .LBB0_876
.Lattn1_skipexit:
	s_cmp_lg_u32 s99, 0
	s_cbranch_scc1 .Lpp1_sxe
	s_barrier
.Lpp1_sxe:
	s_branch .LBB0_874

; #define MFMA(a, b, c) __builtin_amdgcn_mfma_f32_16x16x32_bf16((a), (b), (c), 0, 0, 0)
; template <int MODE> ...
;     ...
; #pragma unroll
;     for (int kh = 0; kh < 2; ++kh) {
; #pragma unroll
;       for (int tt = 0; tt < 2; ++tt) {
;         bf16x8 pf[2];
; #pragma unroll
;         for (int hh = 0; hh < 2; ++hh) {
;           float pv[8];
; #pragma unroll
;           for (int j = 0; j < 4; ++j) {
;             pv[j] = __builtin_amdgcn_exp2f(S[kh][tt][hh][0][j]);
;             pv[4 + j] = __builtin_amdgcn_exp2f(S[kh][tt][hh][1][j]);
;           }
;           lsum[tt][hh] += ((pv[0] + pv[1]) + (pv[2] + pv[3])) + ((pv[4] + pv[5]) + (pv[6] + pv[7]));
;           const uint4 pk = make_uint4(pack2(pv[0], pv[1]), pack2(pv[2], pv[3]), pack2(pv[4], pv[5]), pack2(pv[6], pv[7]));
;           pf[hh] = __builtin_bit_cast(bf16x8, pk);
;         }
; #pragma unroll
;         for (int dt = 0; dt < 4; ++dt) {
;           const bf16x8 vf = *(const bf16x8*)&Vs[(dt * 16 + r) * 64 + (((kh * 4 + g) ^ (r & 7)) * 8)];
;           O[tt][0][dt] = MFMA(vf, pf[0], O[tt][0][dt]);
;           O[tt][1][dt] = MFMA(vf, pf[1], O[tt][1][dt]);
;         }
;       }
;     }
.Lattn1_nw:
	v_exp_f32_e32 v135, v140
	v_exp_f32_e32 v131, v144
	v_exp_f32_e32 v139, v141
	v_exp_f32_e32 v137, v145
	v_exp_f32_e32 v124, v164
	v_exp_f32_e32 v128, v165
	v_exp_f32_e32 v130, v166
	v_exp_f32_e32 v136, v167
	v_pk_add_f32 v[248:249], v[132:133], v[126:127]
	v_pk_add_f32 v[250:251], v[138:139], v[134:135]
	v_pk_add_f32 v[248:249], v[250:251], v[248:249]
	v_pk_add_f32 v[250:251], v[128:129], v[124:125]
	v_pk_add_f32 v[252:253], v[136:137], v[130:131]
	v_pk_add_f32 v[250:251], v[252:253], v[250:251]
	v_pk_add_f32 v[248:249], v[250:251], v[248:249]
	v_pk_add_f32 v[188:189], v[248:249], v[188:189]
	v_cvt_pk_bf16_f32 v240, v126, v132
	v_cvt_pk_bf16_f32 v241, v134, v138
	v_cvt_pk_bf16_f32 v242, v124, v128
	v_cvt_pk_bf16_f32 v243, v130, v136
	v_cvt_pk_bf16_f32 v244, v127, v133
	v_cvt_pk_bf16_f32 v245, v135, v139
	v_cvt_pk_bf16_f32 v246, v125, v129
	v_cvt_pk_bf16_f32 v247, v131, v137
	s_waitcnt lgkmcnt(0)
	s_cmp_lg_u32 s99, 0
	s_cbranch_scc1 .Lpp1_mid
	s_barrier
.Lpp1_mid:
	v_mfma_f32_16x16x32_bf16 v[52:55], v[208:211], v[240:243], v[52:55]
	v_exp_f32_e32 v148, v148
	v_mfma_f32_16x16x32_bf16 v[60:63], v[212:215], v[240:243], v[60:63]
	v_exp_f32_e32 v146, v152
	v_mfma_f32_16x16x32_bf16 v[56:59], v[216:219], v[240:243], v[56:59]
	v_exp_f32_e32 v152, v153
	v_mfma_f32_16x16x32_bf16 v[64:67], v[220:223], v[240:243], v[64:67]
	v_exp_f32_e32 v145, v163
	v_mfma_f32_16x16x32_bf16 v[44:47], v[208:211], v[244:247], v[44:47]
	v_exp_f32_e32 v141, v162
	v_mfma_f32_16x16x32_bf16 v[40:43], v[212:215], v[244:247], v[40:43]
	v_exp_f32_e32 v147, v160
	v_mfma_f32_16x16x32_bf16 v[36:39], v[216:219], v[244:247], v[36:39]
	v_exp_f32_e32 v153, v161
	v_mfma_f32_16x16x32_bf16 v[48:51], v[220:223], v[244:247], v[48:51]
	v_exp_f32_e32 v142, v150
	v_exp_f32_e32 v140, v154
	v_exp_f32_e32 v150, v151
	v_exp_f32_e32 v144, v155
	v_exp_f32_e32 v154, v149
	v_exp_f32_e32 v143, v158
	v_exp_f32_e32 v151, v159
	v_exp_f32_e32 v149, v156
	v_exp_f32_e32 v155, v157
	v_pk_add_f32 v[248:249], v[150:151], v[142:143]
	v_pk_add_f32 v[250:251], v[154:155], v[148:149]
	v_pk_add_f32 v[248:249], v[250:251], v[248:249]
	v_pk_add_f32 v[250:251], v[144:145], v[140:141]
	v_pk_add_f32 v[252:253], v[152:153], v[146:147]
	v_pk_add_f32 v[250:251], v[252:253], v[250:251]
	v_pk_add_f32 v[248:249], v[250:251], v[248:249]
	v_pk_add_f32 v[186:187], v[248:249], v[186:187]
	v_cvt_pk_bf16_f32 v240, v142, v150
	v_cvt_pk_bf16_f32 v241, v148, v154
	v_cvt_pk_bf16_f32 v242, v140, v144
	v_cvt_pk_bf16_f32 v243, v146, v152
	v_cvt_pk_bf16_f32 v244, v143, v151
	v_cvt_pk_bf16_f32 v245, v149, v155
	v_cvt_pk_bf16_f32 v246, v141, v145
	v_cvt_pk_bf16_f32 v247, v147, v153
	v_mfma_f32_16x16x32_bf16 v[32:35], v[208:211], v[240:243], v[32:35]
	v_mfma_f32_16x16x32_bf16 v[28:31], v[212:215], v[240:243], v[28:31]
	v_mfma_f32_16x16x32_bf16 v[24:27], v[216:219], v[240:243], v[24:27]
	v_mfma_f32_16x16x32_bf16 v[20:23], v[220:223], v[240:243], v[20:23]
	v_mfma_f32_16x16x32_bf16 v[16:19], v[208:211], v[244:247], v[16:19]
	v_mfma_f32_16x16x32_bf16 v[12:15], v[212:215], v[244:247], v[12:15]
	v_mfma_f32_16x16x32_bf16 v[8:11], v[216:219], v[244:247], v[8:11]
	v_mfma_f32_16x16x32_bf16 v[4:7], v[220:223], v[244:247], v[4:7]
	s_andn2_b64 vcc, exec, s[56:57]
	s_cbranch_vccz .Lattn1_adv

; template <int MODE> ...
;     ...
;     if (more) {
;       u16* Kn = Kbase + ((it + 1) & 1) * (2 * 64 * 64);
;       *(uint4*)&Kn[kwoff] = kr0;
;       *(uint4*)&Kn[64 * 64 + vwoff] = vr0;
;     }
;   }
.LBB0_887:
	s_and_b32 s48, s2, 0x2000
	s_lshl_b32 s48, s48, 1
	s_add_i32 s48, s48, 32
	v_lshl_add_u32 v91, v165, 1, s48
	v_lshl_add_u32 v90, v190, 1, s48
	s_waitcnt vmcnt(1)
	ds_write_b128 v91, v[50:53]
	s_waitcnt vmcnt(0)
	ds_write_b128 v90, v[54:57] offset:8192
	s_waitcnt lgkmcnt(0)
	s_cmp_lg_u32 s99, 0
	s_cbranch_scc1 .Lpp2_skp
	s_barrier
.Lpp2_skp:
.Lattn2_adv:
	s_addk_i32 s2, 0x2000
	s_add_i32 s45, s45, 64
	s_cmp_lg_u32 s24, s54
	s_cbranch_scc1 .LBB0_895
	s_branch .LBB0_897

; #define MFMA(a, b, c) __builtin_amdgcn_mfma_f32_16x16x32_bf16((a), (b), (c), 0, 0, 0)
; template <int MODE> ...
;     ...
; #pragma unroll
;     for (int kh = 0; kh < 2; ++kh) {
; #pragma unroll
;       for (int tt = 0; tt < 2; ++tt) {
;         bf16x8 pf[2];
; #pragma unroll
;         for (int hh = 0; hh < 2; ++hh) {
;           float pv[8];
; #pragma unroll
;           for (int j = 0; j < 4; ++j) {
;             pv[j] = __builtin_amdgcn_exp2f(S[kh][tt][hh][0][j]);
;             pv[4 + j] = __builtin_amdgcn_exp2f(S[kh][tt][hh][1][j]);
;           }
;           lsum[tt][hh] += ((pv[0] + pv[1]) + (pv[2] + pv[3])) + ((pv[4] + pv[5]) + (pv[6] + pv[7]));
;           const uint4 pk = make_uint4(pack2(pv[0], pv[1]), pack2(pv[2], pv[3]), pack2(pv[4], pv[5]), pack2(pv[6], pv[7]));
;           pf[hh] = __builtin_bit_cast(bf16x8, pk);
;         }
; #pragma unroll
;         for (int dt = 0; dt < 4; ++dt) {
;           const bf16x8 vf = *(const bf16x8*)&Vs[(dt * 16 + r) * 64 + (((kh * 4 + g) ^ (r & 7)) * 8)];
;           O[tt][0][dt] = MFMA(vf, pf[0], O[tt][0][dt]);
;           O[tt][1][dt] = MFMA(vf, pf[1], O[tt][1][dt]);
;         }
;       }
;     }
.Lattn2_nw:
	v_exp_f32_e32 v117, v122
	v_exp_f32_e32 v113, v126
	v_exp_f32_e32 v121, v123
	v_exp_f32_e32 v119, v127
	v_exp_f32_e32 v106, v146
	v_exp_f32_e32 v110, v147
	v_exp_f32_e32 v112, v148
	v_exp_f32_e32 v118, v149
	v_pk_add_f32 v[248:249], v[114:115], v[108:109]
	v_pk_add_f32 v[250:251], v[120:121], v[116:117]
	v_pk_add_f32 v[248:249], v[250:251], v[248:249]
	v_pk_add_f32 v[250:251], v[110:111], v[106:107]
	v_pk_add_f32 v[252:253], v[118:119], v[112:113]
	v_pk_add_f32 v[250:251], v[252:253], v[250:251]
	v_pk_add_f32 v[248:249], v[250:251], v[248:249]
	v_pk_add_f32 v[170:171], v[248:249], v[170:171]
	v_cvt_pk_bf16_f32 v240, v108, v114
	v_cvt_pk_bf16_f32 v241, v116, v120
	v_cvt_pk_bf16_f32 v242, v106, v110
	v_cvt_pk_bf16_f32 v243, v112, v118
	v_cvt_pk_bf16_f32 v244, v109, v115
	v_cvt_pk_bf16_f32 v245, v117, v121
	v_cvt_pk_bf16_f32 v246, v107, v111
	v_cvt_pk_bf16_f32 v247, v113, v119
	s_waitcnt lgkmcnt(0)
	s_cmp_lg_u32 s99, 0
	s_cbranch_scc1 .Lpp2_mid
	s_barrier
.Lpp2_mid:
	v_mfma_f32_16x16x32_bf16 v[70:73], v[200:203], v[240:243], v[70:73]
	v_exp_f32_e32 v130, v130
	v_mfma_f32_16x16x32_bf16 v[78:81], v[204:207], v[240:243], v[78:81]
	v_exp_f32_e32 v128, v134
	v_mfma_f32_16x16x32_bf16 v[62:65], v[208:211], v[240:243], v[62:65]
	v_exp_f32_e32 v134, v135
	v_mfma_f32_16x16x32_bf16 v[74:77], v[212:215], v[240:243], v[74:77]
	v_exp_f32_e32 v127, v145
	v_mfma_f32_16x16x32_bf16 v[86:89], v[200:203], v[244:247], v[86:89]
	v_exp_f32_e32 v123, v144
	v_mfma_f32_16x16x32_bf16 v[66:69], v[204:207], v[244:247], v[66:69]
	v_exp_f32_e32 v129, v142
	v_mfma_f32_16x16x32_bf16 v[58:61], v[208:211], v[244:247], v[58:61]
	v_exp_f32_e32 v135, v143
	v_mfma_f32_16x16x32_bf16 v[82:85], v[212:215], v[244:247], v[82:85]
	v_exp_f32_e32 v124, v132
	v_exp_f32_e32 v122, v136
	v_exp_f32_e32 v132, v133
	v_exp_f32_e32 v126, v137
	v_exp_f32_e32 v136, v131
	v_exp_f32_e32 v125, v140
	v_exp_f32_e32 v133, v141
	v_exp_f32_e32 v131, v138
	v_exp_f32_e32 v137, v139
	v_pk_add_f32 v[248:249], v[132:133], v[124:125]
	v_pk_add_f32 v[250:251], v[136:137], v[130:131]
	v_pk_add_f32 v[248:249], v[250:251], v[248:249]
	v_pk_add_f32 v[250:251], v[126:127], v[122:123]
	v_pk_add_f32 v[252:253], v[134:135], v[128:129]
	v_pk_add_f32 v[250:251], v[252:253], v[250:251]
	v_pk_add_f32 v[248:249], v[250:251], v[248:249]
	v_pk_add_f32 v[156:157], v[248:249], v[156:157]
	v_cvt_pk_bf16_f32 v240, v124, v132
	v_cvt_pk_bf16_f32 v241, v130, v136
	v_cvt_pk_bf16_f32 v242, v122, v126
	v_cvt_pk_bf16_f32 v243, v128, v134
	v_cvt_pk_bf16_f32 v244, v125, v133
	v_cvt_pk_bf16_f32 v245, v131, v137
	v_cvt_pk_bf16_f32 v246, v123, v127
	v_cvt_pk_bf16_f32 v247, v129, v135
	v_mfma_f32_16x16x32_bf16 v[42:45], v[200:203], v[240:243], v[42:45]
	v_mfma_f32_16x16x32_bf16 v[34:37], v[204:207], v[240:243], v[34:37]
	v_mfma_f32_16x16x32_bf16 v[10:13], v[208:211], v[240:243], v[10:13]
	v_mfma_f32_16x16x32_bf16 v[6:9], v[212:215], v[240:243], v[6:9]
	v_mfma_f32_16x16x32_bf16 v[46:49], v[200:203], v[244:247], v[46:49]
	v_mfma_f32_16x16x32_bf16 v[38:41], v[204:207], v[244:247], v[38:41]
	v_mfma_f32_16x16x32_bf16 v[14:17], v[208:211], v[244:247], v[14:17]
	v_mfma_f32_16x16x32_bf16 v[2:5], v[212:215], v[244:247], v[2:5]
	s_andn2_b64 vcc, exec, s[48:49]
	s_cbranch_vccz .Lattn2_adv
